# mode-6 compaction: one LDS atomic per score slot (per-lane counter address select) instead of two exec-masked atomics; lgkmcnt ladder re-derived
# baseline (speedup 1.0000x reference)
;     ...
;         const int kt = kt0 + 4 * (it >> 1), kb = it & 1;
;         const int itn = it + 1 < nit ? it + 1 : it;
;         const bf16_t* np = ikp + (size_t)(256 * (itn >> 1) + 32 * (itn & 1)) * NZ; const bf16x8 n0 = *(const bf16x8*)np, n1 = *(const bf16x8*)(np + 16);
;         f32x2v sc2[8];
; #pragma unroll
;         for (int r = 0; r < 8; ++r) sc2[r] = (f32x2v){0.f, 0.f};
;     ...
;         { f32x16 zero16;
; #pragma unroll
;           for (int r = 0; r < 16; ++r) zero16[r] = 0.f;
;           f32x16 dA0, dA1, dB0, dB1; float wA0, wA1, wB0, wB1;
;           SW_MF(0, dA0, dA1, wA0, wA1);
;           SW_MF(1, dB0, dB1, wB0, wB1); __builtin_amdgcn_sched_barrier(0);
;           SW_VA(dA0, dA1, wA0, wA1);    __builtin_amdgcn_sched_barrier(0);
;           SW_MF(2, dA0, dA1, wA0, wA1); __builtin_amdgcn_sched_barrier(0);
;           SW_VA(dB0, dB1, wB0, wB1);    __builtin_amdgcn_sched_barrier(0);
;           SW_MF(3, dB0, dB1, wB0, wB1); __builtin_amdgcn_sched_barrier(0);
;           SW_VA(dA0, dA1, wA0, wA1);    __builtin_amdgcn_sched_barrier(0);
;           SW_VA(dB0, dB1, wB0, wB1); }
.Lstag_m6:
.Lm6_loop:
	v_mfma_f32_32x32x16_bf16 v[16:31], v[132:135], v[0:3], 0
	v_mfma_f32_32x32x16_bf16 v[16:31], v[128:131], v[4:7], v[16:31]
	ds_read_b128 v[0:3], v165 offset:128
	ds_read_b128 v[4:7], v165 offset:160
	v_mfma_f32_32x32x16_bf16 v[32:47], v[132:135], v[8:11], 0
	v_mfma_f32_32x32x16_bf16 v[32:47], v[128:131], v[12:15], v[32:47]
	ds_read_b128 v[8:11], v165 offset:192
	ds_read_b128 v[12:15], v165 offset:224
	s_add_i32 s1, s18, 1
	s_cmp_lt_u32 s1, s25
	s_cselect_b32 s3, s1, s18
	s_lshl_b32 vcc_lo, s3, 7
	s_and_b32 vcc_lo, vcc_lo, 0x7fffff00
	s_lshl_b32 s3, s3, 5
	s_and_b32 s3, s3, 32
	s_or_b32 s3, vcc_lo, s3
	v_mad_u64_u32 v[114:115], vcc, s3, v223, v[140:141]
	s_lshr_b32 s0, s18, 1
	s_lshl_b32 s0, s0, 2
	s_add_i32 s0, s0, s24
	s_lshl_b32 s0, s0, 6
	s_and_b32 s2, s18, 1
	s_lshl_b32 s2, s2, 5
	s_or_b32 s0, s0, s2
	v_or_b32_e32 v124, s0, v159
	global_load_dwordx4 v[64:67], v[114:115], off
	global_load_dwordx4 v[68:71], v[114:115], off offset:32
	v_pk_mul_f32 v[16:17], v[16:17], v[112:113] clamp
	v_pk_mul_f32 v[18:19], v[18:19], v[112:113] clamp
	v_pk_mul_f32 v[20:21], v[20:21], v[112:113] clamp
	v_pk_mul_f32 v[22:23], v[22:23], v[112:113] clamp
	v_pk_mul_f32 v[24:25], v[24:25], v[112:113] clamp
	v_pk_mul_f32 v[26:27], v[26:27], v[112:113] clamp
	v_pk_mul_f32 v[28:29], v[28:29], v[112:113] clamp
	v_pk_mul_f32 v[30:31], v[30:31], v[112:113] clamp
	v_pk_fma_f32 v[88:89], v[16:17], v[80:81], 0 op_sel_hi:[1,0,0]
	v_pk_fma_f32 v[90:91], v[18:19], v[80:81], 0 op_sel_hi:[1,0,0]
	v_pk_fma_f32 v[92:93], v[20:21], v[80:81], 0 op_sel_hi:[1,0,0]
	v_pk_fma_f32 v[94:95], v[22:23], v[80:81], 0 op_sel_hi:[1,0,0]
	v_pk_fma_f32 v[96:97], v[24:25], v[80:81], 0 op_sel_hi:[1,0,0]
	v_pk_fma_f32 v[98:99], v[26:27], v[80:81], 0 op_sel_hi:[1,0,0]
	v_pk_fma_f32 v[100:101], v[28:29], v[80:81], 0 op_sel_hi:[1,0,0]
	v_pk_fma_f32 v[102:103], v[30:31], v[80:81], 0 op_sel_hi:[1,0,0]
	s_waitcnt lgkmcnt(2)
	v_mfma_f32_32x32x16_bf16 v[16:31], v[132:135], v[0:3], 0
	v_mfma_f32_32x32x16_bf16 v[16:31], v[128:131], v[4:7], v[16:31]
	ds_read_b128 v[0:3], v165 offset:256
	ds_read_b128 v[4:7], v165 offset:288
	v_pk_mul_f32 v[32:33], v[32:33], v[112:113] clamp
	v_pk_mul_f32 v[34:35], v[34:35], v[112:113] clamp
	v_pk_mul_f32 v[36:37], v[36:37], v[112:113] clamp
	v_pk_mul_f32 v[38:39], v[38:39], v[112:113] clamp
	v_pk_mul_f32 v[40:41], v[40:41], v[112:113] clamp
	v_pk_mul_f32 v[42:43], v[42:43], v[112:113] clamp
	v_pk_mul_f32 v[44:45], v[44:45], v[112:113] clamp
	v_pk_mul_f32 v[46:47], v[46:47], v[112:113] clamp
	v_pk_fma_f32 v[88:89], v[32:33], v[104:105], v[88:89] op_sel_hi:[1,0,1]
	v_pk_fma_f32 v[90:91], v[34:35], v[104:105], v[90:91] op_sel_hi:[1,0,1]
	v_pk_fma_f32 v[92:93], v[36:37], v[104:105], v[92:93] op_sel_hi:[1,0,1]
	v_pk_fma_f32 v[94:95], v[38:39], v[104:105], v[94:95] op_sel_hi:[1,0,1]
	v_pk_fma_f32 v[96:97], v[40:41], v[104:105], v[96:97] op_sel_hi:[1,0,1]
	v_pk_fma_f32 v[98:99], v[42:43], v[104:105], v[98:99] op_sel_hi:[1,0,1]
	v_pk_fma_f32 v[100:101], v[44:45], v[104:105], v[100:101] op_sel_hi:[1,0,1]
	v_pk_fma_f32 v[102:103], v[46:47], v[104:105], v[102:103] op_sel_hi:[1,0,1]
	s_waitcnt lgkmcnt(2)
	v_mfma_f32_32x32x16_bf16 v[32:47], v[132:135], v[8:11], 0
	v_mfma_f32_32x32x16_bf16 v[32:47], v[128:131], v[12:15], v[32:47]
	ds_read_b128 v[8:11], v165 offset:320
	ds_read_b128 v[12:15], v165 offset:352
	v_pk_mul_f32 v[16:17], v[16:17], v[112:113] clamp
	v_pk_mul_f32 v[18:19], v[18:19], v[112:113] clamp
	v_pk_mul_f32 v[20:21], v[20:21], v[112:113] clamp
	v_pk_mul_f32 v[22:23], v[22:23], v[112:113] clamp
	v_pk_mul_f32 v[24:25], v[24:25], v[112:113] clamp
	v_pk_mul_f32 v[26:27], v[26:27], v[112:113] clamp
	v_pk_mul_f32 v[28:29], v[28:29], v[112:113] clamp
	v_pk_mul_f32 v[30:31], v[30:31], v[112:113] clamp
	v_pk_fma_f32 v[88:89], v[16:17], v[82:83], v[88:89] op_sel_hi:[1,0,1]
	v_pk_fma_f32 v[90:91], v[18:19], v[82:83], v[90:91] op_sel_hi:[1,0,1]
	v_pk_fma_f32 v[92:93], v[20:21], v[82:83], v[92:93] op_sel_hi:[1,0,1]
	v_pk_fma_f32 v[94:95], v[22:23], v[82:83], v[94:95] op_sel_hi:[1,0,1]
	v_pk_fma_f32 v[96:97], v[24:25], v[82:83], v[96:97] op_sel_hi:[1,0,1]
	v_pk_fma_f32 v[98:99], v[26:27], v[82:83], v[98:99] op_sel_hi:[1,0,1]
	v_pk_fma_f32 v[100:101], v[28:29], v[82:83], v[100:101] op_sel_hi:[1,0,1]
	v_pk_fma_f32 v[102:103], v[30:31], v[82:83], v[102:103] op_sel_hi:[1,0,1]
	s_waitcnt lgkmcnt(2)
	v_mfma_f32_32x32x16_bf16 v[16:31], v[132:135], v[0:3], 0
	v_mfma_f32_32x32x16_bf16 v[16:31], v[128:131], v[4:7], v[16:31]
	ds_read_b128 v[0:3], v165 offset:384
	ds_read_b128 v[4:7], v165 offset:416
	v_pk_mul_f32 v[32:33], v[32:33], v[112:113] clamp
	v_pk_mul_f32 v[34:35], v[34:35], v[112:113] clamp
	v_pk_mul_f32 v[36:37], v[36:37], v[112:113] clamp
	v_pk_mul_f32 v[38:39], v[38:39], v[112:113] clamp
	v_pk_mul_f32 v[40:41], v[40:41], v[112:113] clamp
	v_pk_mul_f32 v[42:43], v[42:43], v[112:113] clamp
	v_pk_mul_f32 v[44:45], v[44:45], v[112:113] clamp
	v_pk_mul_f32 v[46:47], v[46:47], v[112:113] clamp
	v_pk_fma_f32 v[88:89], v[32:33], v[106:107], v[88:89] op_sel_hi:[1,0,1]
	v_pk_fma_f32 v[90:91], v[34:35], v[106:107], v[90:91] op_sel_hi:[1,0,1]
	v_pk_fma_f32 v[92:93], v[36:37], v[106:107], v[92:93] op_sel_hi:[1,0,1]
	v_pk_fma_f32 v[94:95], v[38:39], v[106:107], v[94:95] op_sel_hi:[1,0,1]
	v_pk_fma_f32 v[96:97], v[40:41], v[106:107], v[96:97] op_sel_hi:[1,0,1]
	v_pk_fma_f32 v[98:99], v[42:43], v[106:107], v[98:99] op_sel_hi:[1,0,1]
	v_pk_fma_f32 v[100:101], v[44:45], v[106:107], v[100:101] op_sel_hi:[1,0,1]
	v_pk_fma_f32 v[102:103], v[46:47], v[106:107], v[102:103] op_sel_hi:[1,0,1]
	s_waitcnt lgkmcnt(2)
; __device__ __forceinline__ unsigned sortable(float f) { const unsigned u = __float_as_uint(f); return u ^ ((unsigned)((int)u >> 31) | 0x80000000u); }
; __device__ __forceinline__ int bucketf(float f) { const unsigned u = __float_as_uint(f); const int idx = (int)((u >> 20) & 0x7FFu); const int c = min(max(idx - 816, 128), 255); return c ^ (((int)u >> 31) & 255); }
;     ...
;         { f32x16 zero16;
; #pragma unroll
;           for (int r = 0; r < 16; ++r) zero16[r] = 0.f;
;           f32x16 dA0, dA1, dB0, dB1; float wA0, wA1, wB0, wB1;
;           SW_MF(0, dA0, dA1, wA0, wA1);
;           SW_MF(1, dB0, dB1, wB0, wB1); __builtin_amdgcn_sched_barrier(0);
;           SW_VA(dA0, dA1, wA0, wA1);    __builtin_amdgcn_sched_barrier(0);
;           SW_MF(2, dA0, dA1, wA0, wA1); __builtin_amdgcn_sched_barrier(0);
;           SW_VA(dB0, dB1, wB0, wB1);    __builtin_amdgcn_sched_barrier(0);
;           SW_MF(3, dB0, dB1, wB0, wB1); __builtin_amdgcn_sched_barrier(0);
;           SW_VA(dA0, dA1, wA0, wA1);    __builtin_amdgcn_sched_barrier(0);
;           SW_VA(dB0, dB1, wB0, wB1); }
;     ...
;         for (int r = 0; r < 16; ++r) { const unsigned s = s0 + (unsigned)((r & 3) + 8 * (r >> 2));
;             if (MODE == 5) { __hip_atomic_fetch_add(hist + 64 * bucketf(sc[r]), 1u, __ATOMIC_RELAXED, __HIP_MEMORY_SCOPE_WORKGROUP); continue; }
;             if (MODE == 6) {
;                 if (sc[r] >= t_hi) { const unsigned pos = __hip_atomic_fetch_add(cnt, 1u, __ATOMIC_RELAXED, __HIP_MEMORY_SCOPE_WORKGROUP); sel[pos & 255u] = (unsigned short)s; }
;                 else if (sc[r] >= t_lo) { const unsigned key = (sortable(sc[r]) & 0xFFFFE000u) | (8191u - s);
;                     const unsigned pos = __hip_atomic_fetch_add(ccnt, 1u, __ATOMIC_RELAXED, __HIP_MEMORY_SCOPE_WORKGROUP); cand[pos & (DS_CAP - 1)] = key; }
	v_mfma_f32_32x32x16_bf16 v[32:47], v[132:135], v[8:11], 0
	v_mfma_f32_32x32x16_bf16 v[32:47], v[128:131], v[12:15], v[32:47]
	ds_read_b128 v[8:11], v165 offset:448
	ds_read_b128 v[12:15], v165 offset:480
	v_pk_mul_f32 v[16:17], v[16:17], v[112:113] clamp
	v_pk_mul_f32 v[18:19], v[18:19], v[112:113] clamp
	v_pk_mul_f32 v[20:21], v[20:21], v[112:113] clamp
	v_pk_mul_f32 v[22:23], v[22:23], v[112:113] clamp
	v_pk_mul_f32 v[24:25], v[24:25], v[112:113] clamp
	v_pk_mul_f32 v[26:27], v[26:27], v[112:113] clamp
	v_pk_mul_f32 v[28:29], v[28:29], v[112:113] clamp
	v_pk_mul_f32 v[30:31], v[30:31], v[112:113] clamp
	v_pk_fma_f32 v[88:89], v[16:17], v[84:85], v[88:89] op_sel_hi:[1,0,1]
	v_pk_fma_f32 v[90:91], v[18:19], v[84:85], v[90:91] op_sel_hi:[1,0,1]
	v_pk_fma_f32 v[92:93], v[20:21], v[84:85], v[92:93] op_sel_hi:[1,0,1]
	v_pk_fma_f32 v[94:95], v[22:23], v[84:85], v[94:95] op_sel_hi:[1,0,1]
	v_pk_fma_f32 v[96:97], v[24:25], v[84:85], v[96:97] op_sel_hi:[1,0,1]
	v_pk_fma_f32 v[98:99], v[26:27], v[84:85], v[98:99] op_sel_hi:[1,0,1]
	v_pk_fma_f32 v[100:101], v[28:29], v[84:85], v[100:101] op_sel_hi:[1,0,1]
	v_pk_fma_f32 v[102:103], v[30:31], v[84:85], v[102:103] op_sel_hi:[1,0,1]
	s_waitcnt lgkmcnt(2)
	v_mfma_f32_32x32x16_bf16 v[16:31], v[132:135], v[0:3], 0
	v_mfma_f32_32x32x16_bf16 v[16:31], v[128:131], v[4:7], v[16:31]
	ds_read_b128 v[0:3], v165
	ds_read_b128 v[4:7], v165 offset:32
	v_pk_mul_f32 v[32:33], v[32:33], v[112:113] clamp
	v_pk_mul_f32 v[34:35], v[34:35], v[112:113] clamp
	v_pk_mul_f32 v[36:37], v[36:37], v[112:113] clamp
	v_pk_mul_f32 v[38:39], v[38:39], v[112:113] clamp
	v_pk_mul_f32 v[40:41], v[40:41], v[112:113] clamp
	v_pk_mul_f32 v[42:43], v[42:43], v[112:113] clamp
	v_pk_mul_f32 v[44:45], v[44:45], v[112:113] clamp
	v_pk_mul_f32 v[46:47], v[46:47], v[112:113] clamp
	v_pk_fma_f32 v[88:89], v[32:33], v[108:109], v[88:89] op_sel_hi:[1,0,1]
	v_pk_fma_f32 v[90:91], v[34:35], v[108:109], v[90:91] op_sel_hi:[1,0,1]
	v_pk_fma_f32 v[92:93], v[36:37], v[108:109], v[92:93] op_sel_hi:[1,0,1]
	v_pk_fma_f32 v[94:95], v[38:39], v[108:109], v[94:95] op_sel_hi:[1,0,1]
	v_pk_fma_f32 v[96:97], v[40:41], v[108:109], v[96:97] op_sel_hi:[1,0,1]
	v_pk_fma_f32 v[98:99], v[42:43], v[108:109], v[98:99] op_sel_hi:[1,0,1]
	v_pk_fma_f32 v[100:101], v[44:45], v[108:109], v[100:101] op_sel_hi:[1,0,1]
	v_pk_fma_f32 v[102:103], v[46:47], v[108:109], v[102:103] op_sel_hi:[1,0,1]
	s_waitcnt lgkmcnt(2)
	v_mfma_f32_32x32x16_bf16 v[32:47], v[132:135], v[8:11], 0
	v_mfma_f32_32x32x16_bf16 v[32:47], v[128:131], v[12:15], v[32:47]
	ds_read_b128 v[8:11], v165 offset:64
	ds_read_b128 v[12:15], v165 offset:96
	v_pk_mul_f32 v[16:17], v[16:17], v[112:113] clamp
	v_pk_mul_f32 v[18:19], v[18:19], v[112:113] clamp
	v_pk_mul_f32 v[20:21], v[20:21], v[112:113] clamp
	v_pk_mul_f32 v[22:23], v[22:23], v[112:113] clamp
	v_pk_mul_f32 v[24:25], v[24:25], v[112:113] clamp
	v_pk_mul_f32 v[26:27], v[26:27], v[112:113] clamp
	v_pk_mul_f32 v[28:29], v[28:29], v[112:113] clamp
	v_pk_mul_f32 v[30:31], v[30:31], v[112:113] clamp
	v_pk_fma_f32 v[88:89], v[16:17], v[86:87], v[88:89] op_sel_hi:[1,0,1]
	v_pk_fma_f32 v[90:91], v[18:19], v[86:87], v[90:91] op_sel_hi:[1,0,1]
	v_pk_fma_f32 v[92:93], v[20:21], v[86:87], v[92:93] op_sel_hi:[1,0,1]
	v_pk_fma_f32 v[94:95], v[22:23], v[86:87], v[94:95] op_sel_hi:[1,0,1]
	v_pk_fma_f32 v[96:97], v[24:25], v[86:87], v[96:97] op_sel_hi:[1,0,1]
	v_pk_fma_f32 v[98:99], v[26:27], v[86:87], v[98:99] op_sel_hi:[1,0,1]
	v_pk_fma_f32 v[100:101], v[28:29], v[86:87], v[100:101] op_sel_hi:[1,0,1]
	v_pk_fma_f32 v[102:103], v[30:31], v[86:87], v[102:103] op_sel_hi:[1,0,1]
	v_pk_mul_f32 v[32:33], v[32:33], v[112:113] clamp
	v_pk_mul_f32 v[34:35], v[34:35], v[112:113] clamp
	v_pk_mul_f32 v[36:37], v[36:37], v[112:113] clamp
	v_pk_mul_f32 v[38:39], v[38:39], v[112:113] clamp
	v_pk_mul_f32 v[40:41], v[40:41], v[112:113] clamp
	v_pk_mul_f32 v[42:43], v[42:43], v[112:113] clamp
	v_pk_mul_f32 v[44:45], v[44:45], v[112:113] clamp
	v_pk_mul_f32 v[46:47], v[46:47], v[112:113] clamp
	v_pk_fma_f32 v[88:89], v[32:33], v[110:111], v[88:89] op_sel_hi:[1,0,1]
	v_pk_fma_f32 v[90:91], v[34:35], v[110:111], v[90:91] op_sel_hi:[1,0,1]
	v_pk_fma_f32 v[92:93], v[36:37], v[110:111], v[92:93] op_sel_hi:[1,0,1]
	v_pk_fma_f32 v[94:95], v[38:39], v[110:111], v[94:95] op_sel_hi:[1,0,1]
	v_pk_fma_f32 v[96:97], v[40:41], v[110:111], v[96:97] op_sel_hi:[1,0,1]
	v_pk_fma_f32 v[98:99], v[42:43], v[110:111], v[98:99] op_sel_hi:[1,0,1]
	v_pk_fma_f32 v[100:101], v[44:45], v[110:111], v[100:101] op_sel_hi:[1,0,1]
	v_pk_fma_f32 v[102:103], v[46:47], v[110:111], v[102:103] op_sel_hi:[1,0,1]
	s_waitcnt lgkmcnt(0)
	v_cmp_ge_f32_e64 s[40:41], v88, v122
	v_cmp_ge_f32_e64 s[42:43], v88, v123
	v_mov_b32_e32 v18, v124
	v_cndmask_b32_e64 v56, v171, v180, s[40:41]
	s_mov_b64 exec, s[42:43]
	ds_add_rtn_u32 v16, v56, v222
	s_andn2_b64 s[42:43], s[42:43], s[40:41]
	s_mov_b64 exec, -1
	v_cmp_ge_f32_e64 s[44:45], v89, v122
	v_cmp_ge_f32_e64 s[22:23], v89, v123
	v_or_b32_e32 v19, 1, v124
	v_cndmask_b32_e64 v57, v171, v180, s[44:45]
	s_mov_b64 exec, s[22:23]
	ds_add_rtn_u32 v17, v57, v222
	s_andn2_b64 s[22:23], s[22:23], s[44:45]
	s_mov_b64 exec, -1
	v_cmp_ge_f32_e64 s[20:21], v90, v122
	v_cmp_ge_f32_e64 s[2:3], v90, v123
	v_or_b32_e32 v24, 2, v124
	v_cndmask_b32_e64 v58, v171, v180, s[20:21]
	s_mov_b64 exec, s[2:3]
	ds_add_rtn_u32 v23, v58, v222
	s_andn2_b64 s[2:3], s[2:3], s[20:21]
	s_mov_b64 exec, -1
	s_waitcnt lgkmcnt(2)
	v_and_b32_e32 v16, 0xff, v16
	s_mov_b64 exec, s[40:41]
	v_lshl_add_u32 v20, v16, 1, v179
	ds_write_b16 v20, v18
	s_mov_b64 exec, s[42:43]
	s_cbranch_execz .Lm6_nb0
	v_ashrrev_i32_e32 v22, 31, v88
	v_sub_u32_e32 v18, 0x1fff, v18
	v_lshl_add_u32 v20, v16, 2, v169
	v_bitop3_b32 v21, v22, v88, s64 bitop3:0x36
	v_and_or_b32 v21, v21, s65, v18
	ds_write_b32 v20, v21
; __device__ __forceinline__ unsigned sortable(float f) { const unsigned u = __float_as_uint(f); return u ^ ((unsigned)((int)u >> 31) | 0x80000000u); }
; __device__ __forceinline__ int bucketf(float f) { const unsigned u = __float_as_uint(f); const int idx = (int)((u >> 20) & 0x7FFu); const int c = min(max(idx - 816, 128), 255); return c ^ (((int)u >> 31) & 255); }
;     ...
;         for (int r = 0; r < 16; ++r) { const unsigned s = s0 + (unsigned)((r & 3) + 8 * (r >> 2));
;             if (MODE == 5) { __hip_atomic_fetch_add(hist + 64 * bucketf(sc[r]), 1u, __ATOMIC_RELAXED, __HIP_MEMORY_SCOPE_WORKGROUP); continue; }
;             if (MODE == 6) {
;                 if (sc[r] >= t_hi) { const unsigned pos = __hip_atomic_fetch_add(cnt, 1u, __ATOMIC_RELAXED, __HIP_MEMORY_SCOPE_WORKGROUP); sel[pos & 255u] = (unsigned short)s; }
;                 else if (sc[r] >= t_lo) { const unsigned key = (sortable(sc[r]) & 0xFFFFE000u) | (8191u - s);
;                     const unsigned pos = __hip_atomic_fetch_add(ccnt, 1u, __ATOMIC_RELAXED, __HIP_MEMORY_SCOPE_WORKGROUP); cand[pos & (DS_CAP - 1)] = key; }
;                 continue; }
.Lm6_nb0:
	s_mov_b64 exec, -1
	v_cmp_ge_f32_e64 s[40:41], v91, v122
	v_cmp_ge_f32_e64 s[42:43], v91, v123
	v_or_b32_e32 v18, 3, v124
	v_cndmask_b32_e64 v56, v171, v180, s[40:41]
	s_mov_b64 exec, s[42:43]
	ds_add_rtn_u32 v16, v56, v222
	s_andn2_b64 s[42:43], s[42:43], s[40:41]
	s_mov_b64 exec, -1
	s_waitcnt lgkmcnt(3)
	v_and_b32_e32 v17, 0xff, v17
	s_mov_b64 exec, s[44:45]
	v_lshl_add_u32 v20, v17, 1, v179
	ds_write_b16 v20, v19
	s_mov_b64 exec, s[22:23]
	s_cbranch_execz .Lm6_nb1
	v_ashrrev_i32_e32 v22, 31, v89
	v_sub_u32_e32 v19, 0x1fff, v19
	v_lshl_add_u32 v20, v17, 2, v169
	v_bitop3_b32 v21, v22, v89, s64 bitop3:0x36
	v_and_or_b32 v21, v21, s65, v19
	ds_write_b32 v20, v21
.Lm6_nb1:
	s_mov_b64 exec, -1
	v_cmp_ge_f32_e64 s[44:45], v92, v122
	v_cmp_ge_f32_e64 s[22:23], v92, v123
	v_or_b32_e32 v19, 8, v124
	v_cndmask_b32_e64 v57, v171, v180, s[44:45]
	s_mov_b64 exec, s[22:23]
	ds_add_rtn_u32 v17, v57, v222
	s_andn2_b64 s[22:23], s[22:23], s[44:45]
	s_mov_b64 exec, -1
	s_waitcnt lgkmcnt(4)
	v_and_b32_e32 v23, 0xff, v23
	s_mov_b64 exec, s[20:21]
	v_lshl_add_u32 v20, v23, 1, v179
	ds_write_b16 v20, v24
	s_mov_b64 exec, s[2:3]
	s_cbranch_execz .Lm6_nb2
	v_ashrrev_i32_e32 v22, 31, v90
	v_sub_u32_e32 v24, 0x1fff, v24
	v_lshl_add_u32 v20, v23, 2, v169
	v_bitop3_b32 v21, v22, v90, s64 bitop3:0x36
	v_and_or_b32 v21, v21, s65, v24
	ds_write_b32 v20, v21
.Lm6_nb2:
	s_mov_b64 exec, -1
	v_cmp_ge_f32_e64 s[20:21], v93, v122
	v_cmp_ge_f32_e64 s[2:3], v93, v123
	v_or_b32_e32 v24, 9, v124
	v_cndmask_b32_e64 v58, v171, v180, s[20:21]
	s_mov_b64 exec, s[2:3]
	ds_add_rtn_u32 v23, v58, v222
	s_andn2_b64 s[2:3], s[2:3], s[20:21]
	s_mov_b64 exec, -1
	s_waitcnt lgkmcnt(4)
	v_and_b32_e32 v16, 0xff, v16
	s_mov_b64 exec, s[40:41]
	v_lshl_add_u32 v20, v16, 1, v179
	ds_write_b16 v20, v18
	s_mov_b64 exec, s[42:43]
	s_cbranch_execz .Lm6_nb3
	v_ashrrev_i32_e32 v22, 31, v91
	v_sub_u32_e32 v18, 0x1fff, v18
	v_lshl_add_u32 v20, v16, 2, v169
	v_bitop3_b32 v21, v22, v91, s64 bitop3:0x36
	v_and_or_b32 v21, v21, s65, v18
	ds_write_b32 v20, v21
.Lm6_nb3:
	s_mov_b64 exec, -1
	v_cmp_ge_f32_e64 s[40:41], v94, v122
	v_cmp_ge_f32_e64 s[42:43], v94, v123
	v_or_b32_e32 v18, 10, v124
	v_cndmask_b32_e64 v56, v171, v180, s[40:41]
	s_mov_b64 exec, s[42:43]
	ds_add_rtn_u32 v16, v56, v222
	s_andn2_b64 s[42:43], s[42:43], s[40:41]
	s_mov_b64 exec, -1
	s_waitcnt lgkmcnt(4)
	v_and_b32_e32 v17, 0xff, v17
	s_mov_b64 exec, s[44:45]
	v_lshl_add_u32 v20, v17, 1, v179
	ds_write_b16 v20, v19
	s_mov_b64 exec, s[22:23]
	s_cbranch_execz .Lm6_nb4
	v_ashrrev_i32_e32 v22, 31, v92
	v_sub_u32_e32 v19, 0x1fff, v19
	v_lshl_add_u32 v20, v17, 2, v169
	v_bitop3_b32 v21, v22, v92, s64 bitop3:0x36
	v_and_or_b32 v21, v21, s65, v19
	ds_write_b32 v20, v21
.Lm6_nb4:
	s_mov_b64 exec, -1
	v_cmp_ge_f32_e64 s[44:45], v95, v122
	v_cmp_ge_f32_e64 s[22:23], v95, v123
	v_or_b32_e32 v19, 11, v124
	v_cndmask_b32_e64 v57, v171, v180, s[44:45]
	s_mov_b64 exec, s[22:23]
	ds_add_rtn_u32 v17, v57, v222
	s_andn2_b64 s[22:23], s[22:23], s[44:45]
	s_mov_b64 exec, -1
	s_waitcnt lgkmcnt(4)
	v_and_b32_e32 v23, 0xff, v23
	s_mov_b64 exec, s[20:21]
	v_lshl_add_u32 v20, v23, 1, v179
	ds_write_b16 v20, v24
	s_mov_b64 exec, s[2:3]
	s_cbranch_execz .Lm6_nb5
	v_ashrrev_i32_e32 v22, 31, v93
	v_sub_u32_e32 v24, 0x1fff, v24
	v_lshl_add_u32 v20, v23, 2, v169
	v_bitop3_b32 v21, v22, v93, s64 bitop3:0x36
	v_and_or_b32 v21, v21, s65, v24
	ds_write_b32 v20, v21
.Lm6_nb5:
	s_mov_b64 exec, -1
	v_cmp_ge_f32_e64 s[20:21], v96, v122
	v_cmp_ge_f32_e64 s[2:3], v96, v123
	v_or_b32_e32 v24, 16, v124
	v_cndmask_b32_e64 v58, v171, v180, s[20:21]
	s_mov_b64 exec, s[2:3]
	ds_add_rtn_u32 v23, v58, v222
	s_andn2_b64 s[2:3], s[2:3], s[20:21]
	s_mov_b64 exec, -1
	s_waitcnt lgkmcnt(4)
	v_and_b32_e32 v16, 0xff, v16
	s_mov_b64 exec, s[40:41]
	v_lshl_add_u32 v20, v16, 1, v179
	ds_write_b16 v20, v18
	s_mov_b64 exec, s[42:43]
	s_cbranch_execz .Lm6_nb6
	v_ashrrev_i32_e32 v22, 31, v94
	v_sub_u32_e32 v18, 0x1fff, v18
	v_lshl_add_u32 v20, v16, 2, v169
	v_bitop3_b32 v21, v22, v94, s64 bitop3:0x36
	v_and_or_b32 v21, v21, s65, v18
	ds_write_b32 v20, v21
.Lm6_nb6:
	s_mov_b64 exec, -1
	v_cmp_ge_f32_e64 s[40:41], v97, v122
	v_cmp_ge_f32_e64 s[42:43], v97, v123
	v_or_b32_e32 v18, 17, v124
	v_cndmask_b32_e64 v56, v171, v180, s[40:41]
	s_mov_b64 exec, s[42:43]
	ds_add_rtn_u32 v16, v56, v222
	s_andn2_b64 s[42:43], s[42:43], s[40:41]
	s_mov_b64 exec, -1
	s_waitcnt lgkmcnt(4)
	v_and_b32_e32 v17, 0xff, v17
	s_mov_b64 exec, s[44:45]
	v_lshl_add_u32 v20, v17, 1, v179
	ds_write_b16 v20, v19
	s_mov_b64 exec, s[22:23]
	s_cbranch_execz .Lm6_nb7
	v_ashrrev_i32_e32 v22, 31, v95
	v_sub_u32_e32 v19, 0x1fff, v19
	v_lshl_add_u32 v20, v17, 2, v169
	v_bitop3_b32 v21, v22, v95, s64 bitop3:0x36
	v_and_or_b32 v21, v21, s65, v19
	ds_write_b32 v20, v21
; __device__ __forceinline__ unsigned sortable(float f) { const unsigned u = __float_as_uint(f); return u ^ ((unsigned)((int)u >> 31) | 0x80000000u); }
; __device__ __forceinline__ int bucketf(float f) { const unsigned u = __float_as_uint(f); const int idx = (int)((u >> 20) & 0x7FFu); const int c = min(max(idx - 816, 128), 255); return c ^ (((int)u >> 31) & 255); }
;     ...
;         for (int r = 0; r < 16; ++r) { const unsigned s = s0 + (unsigned)((r & 3) + 8 * (r >> 2));
;             if (MODE == 5) { __hip_atomic_fetch_add(hist + 64 * bucketf(sc[r]), 1u, __ATOMIC_RELAXED, __HIP_MEMORY_SCOPE_WORKGROUP); continue; }
;             if (MODE == 6) {
;                 if (sc[r] >= t_hi) { const unsigned pos = __hip_atomic_fetch_add(cnt, 1u, __ATOMIC_RELAXED, __HIP_MEMORY_SCOPE_WORKGROUP); sel[pos & 255u] = (unsigned short)s; }
;                 else if (sc[r] >= t_lo) { const unsigned key = (sortable(sc[r]) & 0xFFFFE000u) | (8191u - s);
;                     const unsigned pos = __hip_atomic_fetch_add(ccnt, 1u, __ATOMIC_RELAXED, __HIP_MEMORY_SCOPE_WORKGROUP); cand[pos & (DS_CAP - 1)] = key; }
;                 continue; }
.Lm6_nb7:
	s_mov_b64 exec, -1
	v_cmp_ge_f32_e64 s[44:45], v98, v122
	v_cmp_ge_f32_e64 s[22:23], v98, v123
	v_or_b32_e32 v19, 18, v124
	v_cndmask_b32_e64 v57, v171, v180, s[44:45]
	s_mov_b64 exec, s[22:23]
	ds_add_rtn_u32 v17, v57, v222
	s_andn2_b64 s[22:23], s[22:23], s[44:45]
	s_mov_b64 exec, -1
	s_waitcnt lgkmcnt(4)
	v_and_b32_e32 v23, 0xff, v23
	s_mov_b64 exec, s[20:21]
	v_lshl_add_u32 v20, v23, 1, v179
	ds_write_b16 v20, v24
	s_mov_b64 exec, s[2:3]
	s_cbranch_execz .Lm6_nb8
	v_ashrrev_i32_e32 v22, 31, v96
	v_sub_u32_e32 v24, 0x1fff, v24
	v_lshl_add_u32 v20, v23, 2, v169
	v_bitop3_b32 v21, v22, v96, s64 bitop3:0x36
	v_and_or_b32 v21, v21, s65, v24
	ds_write_b32 v20, v21
.Lm6_nb8:
	s_mov_b64 exec, -1
	v_cmp_ge_f32_e64 s[20:21], v99, v122
	v_cmp_ge_f32_e64 s[2:3], v99, v123
	v_or_b32_e32 v24, 19, v124
	v_cndmask_b32_e64 v58, v171, v180, s[20:21]
	s_mov_b64 exec, s[2:3]
	ds_add_rtn_u32 v23, v58, v222
	s_andn2_b64 s[2:3], s[2:3], s[20:21]
	s_mov_b64 exec, -1
	s_waitcnt lgkmcnt(4)
	v_and_b32_e32 v16, 0xff, v16
	s_mov_b64 exec, s[40:41]
	v_lshl_add_u32 v20, v16, 1, v179
	ds_write_b16 v20, v18
	s_mov_b64 exec, s[42:43]
	s_cbranch_execz .Lm6_nb9
	v_ashrrev_i32_e32 v22, 31, v97
	v_sub_u32_e32 v18, 0x1fff, v18
	v_lshl_add_u32 v20, v16, 2, v169
	v_bitop3_b32 v21, v22, v97, s64 bitop3:0x36
	v_and_or_b32 v21, v21, s65, v18
	ds_write_b32 v20, v21
.Lm6_nb9:
	s_mov_b64 exec, -1
	v_cmp_ge_f32_e64 s[40:41], v100, v122
	v_cmp_ge_f32_e64 s[42:43], v100, v123
	v_or_b32_e32 v18, 24, v124
	v_cndmask_b32_e64 v56, v171, v180, s[40:41]
	s_mov_b64 exec, s[42:43]
	ds_add_rtn_u32 v16, v56, v222
	s_andn2_b64 s[42:43], s[42:43], s[40:41]
	s_mov_b64 exec, -1
	s_waitcnt lgkmcnt(4)
	v_and_b32_e32 v17, 0xff, v17
	s_mov_b64 exec, s[44:45]
	v_lshl_add_u32 v20, v17, 1, v179
	ds_write_b16 v20, v19
	s_mov_b64 exec, s[22:23]
	s_cbranch_execz .Lm6_nb10
	v_ashrrev_i32_e32 v22, 31, v98
	v_sub_u32_e32 v19, 0x1fff, v19
	v_lshl_add_u32 v20, v17, 2, v169
	v_bitop3_b32 v21, v22, v98, s64 bitop3:0x36
	v_and_or_b32 v21, v21, s65, v19
	ds_write_b32 v20, v21
.Lm6_nb10:
	s_mov_b64 exec, -1
	v_cmp_ge_f32_e64 s[44:45], v101, v122
	v_cmp_ge_f32_e64 s[22:23], v101, v123
	v_or_b32_e32 v19, 25, v124
	v_cndmask_b32_e64 v57, v171, v180, s[44:45]
	s_mov_b64 exec, s[22:23]
	ds_add_rtn_u32 v17, v57, v222
	s_andn2_b64 s[22:23], s[22:23], s[44:45]
	s_mov_b64 exec, -1
	s_waitcnt lgkmcnt(4)
	v_and_b32_e32 v23, 0xff, v23
	s_mov_b64 exec, s[20:21]
	v_lshl_add_u32 v20, v23, 1, v179
	ds_write_b16 v20, v24
	s_mov_b64 exec, s[2:3]
	s_cbranch_execz .Lm6_nb11
	v_ashrrev_i32_e32 v22, 31, v99
	v_sub_u32_e32 v24, 0x1fff, v24
	v_lshl_add_u32 v20, v23, 2, v169
	v_bitop3_b32 v21, v22, v99, s64 bitop3:0x36
	v_and_or_b32 v21, v21, s65, v24
	ds_write_b32 v20, v21
.Lm6_nb11:
	s_mov_b64 exec, -1
	v_cmp_ge_f32_e64 s[20:21], v102, v122
	v_cmp_ge_f32_e64 s[2:3], v102, v123
	v_or_b32_e32 v24, 26, v124
	v_cndmask_b32_e64 v58, v171, v180, s[20:21]
	s_mov_b64 exec, s[2:3]
	ds_add_rtn_u32 v23, v58, v222
	s_andn2_b64 s[2:3], s[2:3], s[20:21]
	s_mov_b64 exec, -1
	s_waitcnt lgkmcnt(4)
	v_and_b32_e32 v16, 0xff, v16
	s_mov_b64 exec, s[40:41]
	v_lshl_add_u32 v20, v16, 1, v179
	ds_write_b16 v20, v18
	s_mov_b64 exec, s[42:43]
	s_cbranch_execz .Lm6_nb12
	v_ashrrev_i32_e32 v22, 31, v100
	v_sub_u32_e32 v18, 0x1fff, v18
	v_lshl_add_u32 v20, v16, 2, v169
	v_bitop3_b32 v21, v22, v100, s64 bitop3:0x36
	v_and_or_b32 v21, v21, s65, v18
	ds_write_b32 v20, v21
.Lm6_nb12:
	s_mov_b64 exec, -1
	v_cmp_ge_f32_e64 s[40:41], v103, v122
	v_cmp_ge_f32_e64 s[42:43], v103, v123
	v_or_b32_e32 v18, 27, v124
	v_cndmask_b32_e64 v56, v171, v180, s[40:41]
	s_mov_b64 exec, s[42:43]
	ds_add_rtn_u32 v16, v56, v222
	s_andn2_b64 s[42:43], s[42:43], s[40:41]
	s_mov_b64 exec, -1
	s_waitcnt lgkmcnt(4)
	v_and_b32_e32 v17, 0xff, v17
	s_mov_b64 exec, s[44:45]
	v_lshl_add_u32 v20, v17, 1, v179
	ds_write_b16 v20, v19
	s_mov_b64 exec, s[22:23]
	s_cbranch_execz .Lm6_nb13
	v_ashrrev_i32_e32 v22, 31, v101
	v_sub_u32_e32 v19, 0x1fff, v19
	v_lshl_add_u32 v20, v17, 2, v169
	v_bitop3_b32 v21, v22, v101, s64 bitop3:0x36
	v_and_or_b32 v21, v21, s65, v19
	ds_write_b32 v20, v21
.Lm6_nb13:
	s_mov_b64 exec, -1
	s_waitcnt lgkmcnt(3)
	v_and_b32_e32 v23, 0xff, v23
	s_mov_b64 exec, s[20:21]
	v_lshl_add_u32 v20, v23, 1, v179
	ds_write_b16 v20, v24
	s_mov_b64 exec, s[2:3]
	s_cbranch_execz .Lm6_nb14
	v_ashrrev_i32_e32 v22, 31, v102
	v_sub_u32_e32 v24, 0x1fff, v24
	v_lshl_add_u32 v20, v23, 2, v169
	v_bitop3_b32 v21, v22, v102, s64 bitop3:0x36
	v_and_or_b32 v21, v21, s65, v24
	ds_write_b32 v20, v21
